# restored max(0,1-a^2) guard before sqrt in the RNN gate epilogue (robustness for exp2 rounding above 1)
# baseline (speedup 1.0000x reference)
.Lrnn_wd:
	ds_write_b16 v175, v120
	ds_write_b16_d16_hi v175, v120 offset:272
	ds_write_b16 v175, v121 offset:544
	ds_write_b16_d16_hi v175, v121 offset:816
	ds_write_b16 v175, v122 offset:1088
	ds_write_b16_d16_hi v175, v122 offset:1360
	ds_write_b16 v175, v123 offset:1632
	ds_write_b16_d16_hi v175, v123 offset:1904
	s_nop 0
	global_load_dwordx4 v[120:123], v2, s[100:101]
	global_store_dwordx4 v[182:183], v[148:151], off
	v_cvt_pk_bf16_f32 v140, v140, v141
	v_cvt_pk_bf16_f32 v141, v142, v143
	v_cvt_pk_bf16_f32 v142, v160, v161
	v_cvt_pk_bf16_f32 v143, v162, v163
	v_cndmask_b32_e32 v229, 0, v140, vcc
	v_cndmask_b32_e32 v230, 0, v141, vcc
	v_mfma_f32_16x16x32_bf16 v[156:159], v[52:55], v[140:143], 0
	v_cndmask_b32_e32 v184, 0, v142, vcc
	v_cndmask_b32_e32 v185, 0, v143, vcc
	v_mfma_f32_16x16x32_bf16 v[144:147], v[68:71], v[140:143], 0
	v_mfma_f32_16x16x32_bf16 v[148:151], v[84:87], v[140:143], 0
	v_mfma_f32_16x16x32_bf16 v[152:155], v[100:103], v[140:143], 0
	s_waitcnt lgkmcnt(12)
	v_mfma_f32_16x16x32_bf16 v[200:203], v[20:23], v[190:193], v[200:203]
	s_waitcnt lgkmcnt(9)
	v_mfma_f32_16x16x32_bf16 v[164:167], v[28:31], v[242:245], v[164:167]
	v_mfma_f32_16x16x32_bf16 v[200:203], v[24:27], v[238:241], v[200:203]
	s_waitcnt lgkmcnt(0)
	v_mfma_f32_16x16x32_bf16 v[164:167], v[32:35], v[246:249], v[164:167]
	ds_read_b128 v[140:143], v204 offset:256
	ds_read_b128 v[190:193], v205 offset:128
	ds_read_b128 v[238:241], v205 offset:144
	ds_read_b128 v[160:163], v204 offset:320
	ds_read_b128 v[242:245], v205 offset:160
	ds_read_b128 v[246:249], v205 offset:176
	ds_read_b128 v[214:217], v206
	ds_read_b128 v[218:221], v207
	s_nop 1
	v_cvt_pk_bf16_f32 v200, v200, v201
	v_cvt_pk_bf16_f32 v201, v202, v203
	v_cvt_pk_bf16_f32 v202, v164, v165
	v_cvt_pk_bf16_f32 v203, v166, v167
	v_cndmask_b32_e64 v229, v229, v200, s[40:41]
	v_cndmask_b32_e64 v230, v230, v201, s[40:41]
	v_mfma_f32_16x16x32_bf16 v[156:159], v[56:59], v[200:203], v[156:159]
	v_cndmask_b32_e64 v184, v184, v202, s[40:41]
	v_cndmask_b32_e64 v185, v185, v203, s[40:41]
	v_mfma_f32_16x16x32_bf16 v[144:147], v[72:75], v[200:203], v[144:147]
	v_mfma_f32_16x16x32_bf16 v[148:151], v[88:91], v[200:203], v[148:151]
	v_mfma_f32_16x16x32_bf16 v[152:155], v[104:107], v[200:203], v[152:155]
	s_waitcnt lgkmcnt(6)
	v_mfma_f32_16x16x32_bf16 v[140:143], v[36:39], v[190:193], v[140:143]
	s_waitcnt lgkmcnt(3)
	v_mfma_f32_16x16x32_bf16 v[160:163], v[44:47], v[242:245], v[160:163]
	v_mfma_f32_16x16x32_bf16 v[140:143], v[40:43], v[238:241], v[140:143]
	s_waitcnt lgkmcnt(2)
	v_mfma_f32_16x16x32_bf16 v[160:163], v[48:51], v[246:249], v[160:163]
	ds_read_b128 v[200:203], v204 offset:384
	ds_read_b128 v[190:193], v205 offset:192
	ds_read_b128 v[238:241], v205 offset:208
	ds_read_b128 v[164:167], v204 offset:448
	ds_read_b128 v[242:245], v205 offset:224
	ds_read_b128 v[246:249], v205 offset:240
	s_nop 3
	v_cvt_pk_bf16_f32 v140, v140, v141
	v_cvt_pk_bf16_f32 v141, v142, v143
	v_cvt_pk_bf16_f32 v142, v160, v161
	v_cvt_pk_bf16_f32 v143, v162, v163
	v_cndmask_b32_e64 v229, v229, v140, s[42:43]
	v_cndmask_b32_e64 v230, v230, v141, s[42:43]
	v_mfma_f32_16x16x32_bf16 v[156:159], v[60:63], v[140:143], v[156:159]
	v_cndmask_b32_e64 v184, v184, v142, s[42:43]
	v_cndmask_b32_e64 v185, v185, v143, s[42:43]
	v_mfma_f32_16x16x32_bf16 v[144:147], v[76:79], v[140:143], v[144:147]
	v_mfma_f32_16x16x32_bf16 v[148:151], v[92:95], v[140:143], v[148:151]
	v_mfma_f32_16x16x32_bf16 v[152:155], v[108:111], v[140:143], v[152:155]
	ds_read_b128 v[140:143], v208
	ds_read_b128 v[160:163], v209
	s_waitcnt lgkmcnt(6)
	v_mfma_f32_16x16x32_bf16 v[200:203], v[214:217], v[190:193], v[200:203]
	s_waitcnt lgkmcnt(3)
	v_mfma_f32_16x16x32_bf16 v[164:167], v[218:221], v[242:245], v[164:167]
	s_waitcnt lgkmcnt(1)
	v_mfma_f32_16x16x32_bf16 v[200:203], v[140:143], v[238:241], v[200:203]
	s_waitcnt lgkmcnt(0)
	v_mfma_f32_16x16x32_bf16 v[164:167], v[160:163], v[246:249], v[164:167]
	ds_read_b128 v[190:193], v210
	ds_read_b128 v[238:241], v210 offset:128
	ds_read_b128 v[242:245], v210 offset:256
	ds_read_b128 v[246:249], v210 offset:64
	ds_read_b128 v[214:217], v210 offset:192
	ds_read_b128 v[218:221], v210 offset:320
	s_nop 3
	v_cvt_pk_bf16_f32 v200, v200, v201
	v_cvt_pk_bf16_f32 v201, v202, v203
	v_cvt_pk_bf16_f32 v202, v164, v165
	v_cvt_pk_bf16_f32 v203, v166, v167
	v_cndmask_b32_e64 v229, v229, v200, s[44:45]
	v_cndmask_b32_e64 v230, v230, v201, s[44:45]
	v_mfma_f32_16x16x32_bf16 v[156:159], v[64:67], v[200:203], v[156:159]
	v_cndmask_b32_e64 v184, v184, v202, s[44:45]
	v_cndmask_b32_e64 v185, v185, v203, s[44:45]
	v_mfma_f32_16x16x32_bf16 v[144:147], v[80:83], v[200:203], v[144:147]
	v_mfma_f32_16x16x32_bf16 v[148:151], v[96:99], v[200:203], v[148:151]
	v_mfma_f32_16x16x32_bf16 v[152:155], v[112:115], v[200:203], v[152:155]
	v_lshlrev_b32_e32 v231, 16, v229
	v_and_b32_e32 v229, 0xffff0000, v229
	v_lshlrev_b32_e32 v232, 16, v230
	v_and_b32_e32 v230, 0xffff0000, v230
	v_lshlrev_b32_e32 v172, 16, v184
	v_and_b32_e32 v184, 0xffff0000, v184
	v_lshlrev_b32_e32 v3, 16, v185
	v_and_b32_e32 v185, 0xffff0000, v185
	s_nop 1
	s_waitcnt lgkmcnt(5)
	v_add_f32_e32 v156, v156, v190
	v_add_f32_e32 v157, v157, v191
	v_add_f32_e32 v158, v158, v192
	v_add_f32_e32 v159, v159, v193
	s_waitcnt lgkmcnt(4)
	v_add_f32_e32 v148, v148, v238
	v_add_f32_e32 v149, v149, v239
	v_add_f32_e32 v150, v150, v240
	v_add_f32_e32 v151, v151, v241
	v_exp_f32_e32 v156, v156
	v_exp_f32_e32 v157, v157
	v_exp_f32_e32 v158, v158
	v_exp_f32_e32 v159, v159
	v_exp_f32_e32 v148, v148
	v_exp_f32_e32 v149, v149
	v_exp_f32_e32 v150, v150
	v_exp_f32_e32 v151, v151
	s_waitcnt lgkmcnt(2)
	v_add_f32_e32 v144, v144, v246
	v_add_f32_e32 v145, v145, v247
	v_add_f32_e32 v146, v146, v248
	v_add_f32_e32 v147, v147, v249
	s_waitcnt lgkmcnt(1)
	v_add_f32_e32 v152, v152, v214
	v_add_f32_e32 v153, v153, v215
	v_add_f32_e32 v154, v154, v216
	v_add_f32_e32 v155, v155, v217
	v_exp_f32_e32 v144, v144
	v_exp_f32_e32 v145, v145
	v_exp_f32_e32 v146, v146
	v_exp_f32_e32 v147, v147
	v_exp_f32_e32 v152, v152
	v_exp_f32_e32 v153, v153
	v_exp_f32_e32 v154, v154
	v_exp_f32_e32 v155, v155
	v_add_f32_e32 v156, 1.0, v156
	v_add_f32_e32 v157, 1.0, v157
	v_add_f32_e32 v158, 1.0, v158
	v_add_f32_e32 v159, 1.0, v159
	v_add_f32_e32 v144, 1.0, v144
	v_add_f32_e32 v145, 1.0, v145
	v_add_f32_e32 v146, 1.0, v146
	v_add_f32_e32 v147, 1.0, v147
	v_add_f32_e32 v148, 1.0, v148
	v_add_f32_e32 v149, 1.0, v149
	v_add_f32_e32 v150, 1.0, v150
	v_add_f32_e32 v151, 1.0, v151
	v_add_f32_e32 v152, 1.0, v152
	v_add_f32_e32 v153, 1.0, v153
	v_add_f32_e32 v154, 1.0, v154
	v_add_f32_e32 v155, 1.0, v155
	v_rcp_f32_e64 v156, -v156
	v_rcp_f32_e64 v157, -v157
	v_rcp_f32_e64 v158, -v158
	v_rcp_f32_e64 v159, -v159
	v_rcp_f32_e64 v144, -v144
	v_rcp_f32_e64 v145, -v145
	v_rcp_f32_e64 v146, -v146
	v_rcp_f32_e64 v147, -v147
	v_rcp_f32_e32 v148, v148
	v_rcp_f32_e32 v149, v149
	v_rcp_f32_e32 v150, v150
	v_rcp_f32_e32 v151, v151
	v_rcp_f32_e32 v152, v152
	v_rcp_f32_e32 v153, v153
	v_rcp_f32_e32 v154, v154
	v_rcp_f32_e32 v155, v155
	s_waitcnt lgkmcnt(0)
	v_mul_f32_e32 v156, v242, v156
	v_mul_f32_e32 v157, v243, v157
	v_mul_f32_e32 v158, v244, v158
	v_mul_f32_e32 v159, v245, v159
	v_mul_f32_e32 v144, v218, v144
	v_mul_f32_e32 v145, v219, v145
	v_mul_f32_e32 v146, v220, v146
	v_mul_f32_e32 v147, v221, v147
	v_mul_f32_e32 v148, v148, v231
	v_mul_f32_e32 v149, v149, v229
	v_mul_f32_e32 v150, v150, v232
	v_mul_f32_e32 v151, v151, v230
	v_mul_f32_e32 v152, v152, v172
	v_mul_f32_e32 v153, v153, v184
	v_mul_f32_e32 v154, v154, v3
	v_mul_f32_e32 v155, v155, v185
	v_exp_f32_e32 v238, v156
	v_exp_f32_e32 v240, v157
	v_exp_f32_e32 v242, v158
	v_exp_f32_e32 v244, v159
	v_exp_f32_e32 v214, v144
	v_exp_f32_e32 v216, v145
	v_exp_f32_e32 v218, v146
	v_exp_f32_e32 v220, v147
	v_fma_f32 v190, -v238, v238, 1.0
	v_fma_f32 v191, -v240, v240, 1.0
	v_fma_f32 v192, -v242, v242, 1.0
	v_fma_f32 v193, -v244, v244, 1.0
	v_fma_f32 v246, -v214, v214, 1.0
	v_fma_f32 v247, -v216, v216, 1.0
	v_fma_f32 v248, -v218, v218, 1.0
	v_fma_f32 v249, -v220, v220, 1.0
	v_max_f32_e32 v190, 0, v190
	v_max_f32_e32 v191, 0, v191
	v_max_f32_e32 v192, 0, v192
	v_max_f32_e32 v193, 0, v193
	v_max_f32_e32 v246, 0, v246
	v_max_f32_e32 v247, 0, v247
	v_max_f32_e32 v248, 0, v248
	v_max_f32_e32 v249, 0, v249
	v_sqrt_f32_e32 v190, v190
	v_sqrt_f32_e32 v191, v191
	v_sqrt_f32_e32 v192, v192
	v_sqrt_f32_e32 v193, v193
	v_sqrt_f32_e32 v246, v246
	v_sqrt_f32_e32 v247, v247
	v_sqrt_f32_e32 v248, v248
	v_sqrt_f32_e32 v249, v249
	v_mul_f32_e32 v239, v148, v190
	v_mul_f32_e32 v241, v149, v191
	v_mul_f32_e32 v243, v150, v192
	v_mul_f32_e32 v245, v151, v193
	v_mul_f32_e32 v215, v152, v246
	v_mul_f32_e32 v217, v153, v247
	v_mul_f32_e32 v219, v154, v248
	v_mul_f32_e32 v221, v155, v249
	ds_write_b64 v213, v[238:239]
	ds_write_b64 v213, v[240:241] offset:1088
	ds_write_b64 v213, v[242:243] offset:2176
	ds_write_b64 v213, v[244:245] offset:3264
	ds_write_b64 v213, v[214:215] offset:17408
	ds_write_b64 v213, v[216:217] offset:18496
	ds_write_b64 v213, v[218:219] offset:19584
	ds_write_b64 v213, v[220:221] offset:20672
	v_mov_b32_e32 v161, 0
	s_waitcnt lgkmcnt(0)
	s_barrier
	ds_read_b128 v[148:151], v224
	ds_read_b128 v[152:155], v224 offset:16
	ds_read_b128 v[144:147], v224 offset:32
	ds_read_b128 v[140:143], v224 offset:48
	s_waitcnt vmcnt(2)
	ds_write_b128 v177, v[124:127] offset:816
	ds_write_b128 v179, v[128:131] offset:816
	ds_write_b128 v181, v[132:135] offset:816
	ds_write_b128 v199, v[136:139] offset:816
	s_and_saveexec_b64 s[10:11], s[38:39]
	s_cbranch_execz .Lrnn_halo_done
	ds_write_b128 v177, v[116:119]
